# GEMM EpiBf16Rs: row-scale loads issued before the K-loop into free VGPRs, epilogue opens with vmcnt(8) instead of a vmcnt(0) drain
# speedup vs baseline: 1.0040x; 1.0040x over previous
.LBB0_169:
	v_lshl_add_u32 v244, s80, 8, v133
	v_readlane_b32 s100, v253, 49
	v_ashrrev_i32_e32 v245, 31, v244
	v_readlane_b32 s101, v253, 50
	s_nop 1
	v_lshl_add_u64 v[244:245], v[244:245], 2, s[100:101]
	global_load_dword v236, v[244:245], off offset:64
	global_load_dword v237, v[244:245], off offset:128
	global_load_dword v238, v[244:245], off offset:192
	global_load_dword v239, v[244:245], off offset:512
	global_load_dword v240, v[244:245], off offset:576
	global_load_dword v241, v[244:245], off offset:640
	global_load_dword v242, v[244:245], off offset:704
	global_load_dword v243, v[244:245], off
	s_ashr_i32 s47, s46, 31
	s_lshl_b64 s[68:69], s[46:47], 21
	s_add_u32 s68, s39, s68
	s_addc_u32 s69, s43, s69
	s_and_b64 s[74:75], s[52:53], exec
	s_cselect_b32 s47, s69, s71
	s_cselect_b32 s74, s68, s70
	s_ashr_i32 s7, s6, 31
	s_lshl_b64 s[78:79], s[6:7], 21
	s_add_u32 s78, s37, s78
	s_addc_u32 s79, s38, s79
	s_and_b64 s[84:85], s[52:53], exec
	s_cselect_b32 s7, s79, s73
	s_cselect_b32 s75, s78, s72
	s_add_u32 s70, s70, 0x100080
	s_addc_u32 s71, s71, 0
	s_add_u32 s77, s72, 0x100
	v_mov_b32_e32 v0, 0
	s_addc_u32 s81, s73, 0
	s_mov_b32 s84, -2
	v_mov_b32_e32 v1, v0
	v_mov_b32_e32 v2, v0
	v_mov_b32_e32 v3, v0
	v_mov_b32_e32 v4, v0
	v_mov_b32_e32 v5, v0
	v_mov_b32_e32 v6, v0
	v_mov_b32_e32 v7, v0
	v_mov_b32_e32 v16, v0
	v_mov_b32_e32 v17, v0
	v_mov_b32_e32 v18, v0
	v_mov_b32_e32 v19, v0
	v_mov_b32_e32 v20, v0
	v_mov_b32_e32 v21, v0
	v_mov_b32_e32 v22, v0
	v_mov_b32_e32 v23, v0
	v_mov_b32_e32 v32, v0
	v_mov_b32_e32 v33, v0
	v_mov_b32_e32 v34, v0
	v_mov_b32_e32 v35, v0
	v_mov_b32_e32 v36, v0
	v_mov_b32_e32 v37, v0
	v_mov_b32_e32 v38, v0
	v_mov_b32_e32 v39, v0
	v_mov_b32_e32 v48, v0
	v_mov_b32_e32 v49, v0
	v_mov_b32_e32 v50, v0
	v_mov_b32_e32 v51, v0
	v_mov_b32_e32 v52, v0
	v_mov_b32_e32 v53, v0
	v_mov_b32_e32 v54, v0
	v_mov_b32_e32 v55, v0
	v_mov_b32_e32 v8, v0
	v_mov_b32_e32 v9, v0
	v_mov_b32_e32 v10, v0
	v_mov_b32_e32 v11, v0
	v_mov_b32_e32 v12, v0
	v_mov_b32_e32 v13, v0
	v_mov_b32_e32 v14, v0
	v_mov_b32_e32 v15, v0
	v_mov_b32_e32 v24, v0
	v_mov_b32_e32 v25, v0
	v_mov_b32_e32 v26, v0
	v_mov_b32_e32 v27, v0
	v_mov_b32_e32 v28, v0
	v_mov_b32_e32 v29, v0
	v_mov_b32_e32 v30, v0
	v_mov_b32_e32 v31, v0
	v_mov_b32_e32 v40, v0
	v_mov_b32_e32 v41, v0
	v_mov_b32_e32 v42, v0
	v_mov_b32_e32 v43, v0
	v_mov_b32_e32 v44, v0
	v_mov_b32_e32 v45, v0
	v_mov_b32_e32 v46, v0
	v_mov_b32_e32 v47, v0
	v_mov_b32_e32 v56, v0
	v_mov_b32_e32 v57, v0
	v_mov_b32_e32 v58, v0
	v_mov_b32_e32 v59, v0
	v_mov_b32_e32 v60, v0
	v_mov_b32_e32 v61, v0
	v_mov_b32_e32 v62, v0
	v_mov_b32_e32 v63, v0
	v_mov_b32_e32 v64, v0
	v_mov_b32_e32 v65, v0
	v_mov_b32_e32 v66, v0
	v_mov_b32_e32 v67, v0
	v_mov_b32_e32 v68, v0
	v_mov_b32_e32 v69, v0
	v_mov_b32_e32 v70, v0
	v_mov_b32_e32 v71, v0
	v_mov_b32_e32 v80, v0
	v_mov_b32_e32 v81, v0
	v_mov_b32_e32 v82, v0
	v_mov_b32_e32 v83, v0
	v_mov_b32_e32 v84, v0
	v_mov_b32_e32 v85, v0
	v_mov_b32_e32 v86, v0
	v_mov_b32_e32 v87, v0
	v_mov_b32_e32 v96, v0
	v_mov_b32_e32 v97, v0
	v_mov_b32_e32 v98, v0
	v_mov_b32_e32 v99, v0
	v_mov_b32_e32 v100, v0
	v_mov_b32_e32 v101, v0
	v_mov_b32_e32 v102, v0
	v_mov_b32_e32 v103, v0
	v_mov_b32_e32 v112, v0
	v_mov_b32_e32 v113, v0
	v_mov_b32_e32 v114, v0
	v_mov_b32_e32 v115, v0
	v_mov_b32_e32 v116, v0
	v_mov_b32_e32 v117, v0
	v_mov_b32_e32 v118, v0
	v_mov_b32_e32 v119, v0
	v_mov_b32_e32 v72, v0
	v_mov_b32_e32 v73, v0
	v_mov_b32_e32 v74, v0
	v_mov_b32_e32 v75, v0
	v_mov_b32_e32 v76, v0
	v_mov_b32_e32 v77, v0
	v_mov_b32_e32 v78, v0
	v_mov_b32_e32 v79, v0
	v_mov_b32_e32 v88, v0
	v_mov_b32_e32 v89, v0
	v_mov_b32_e32 v90, v0
	v_mov_b32_e32 v91, v0
	v_mov_b32_e32 v92, v0
	v_mov_b32_e32 v93, v0
	v_mov_b32_e32 v94, v0
	v_mov_b32_e32 v95, v0
	v_mov_b32_e32 v104, v0
	v_mov_b32_e32 v105, v0
	v_mov_b32_e32 v106, v0
	v_mov_b32_e32 v107, v0
	v_mov_b32_e32 v108, v0
	v_mov_b32_e32 v109, v0
	v_mov_b32_e32 v110, v0
	v_mov_b32_e32 v111, v0
	v_mov_b32_e32 v120, v0
	v_mov_b32_e32 v121, v0
	v_mov_b32_e32 v122, v0
	v_mov_b32_e32 v123, v0
	v_mov_b32_e32 v124, v0
	v_mov_b32_e32 v125, v0
	v_mov_b32_e32 v126, v0
	v_mov_b32_e32 v127, v0

.LBB0_173:
	v_lshl_add_u32 v158, s80, 8, v133
	v_readlane_b32 s70, v253, 49
	v_ashrrev_i32_e32 v159, 31, v158
	v_readlane_b32 s71, v253, 50
	v_lshl_or_b32 v134, s42, 8, v139
	v_ashrrev_i32_e32 v135, 31, v134
	v_mov_b32_e32 v152, v236
	v_mov_b32_e32 v160, v237
	v_mov_b32_e32 v142, v238
	v_mov_b32_e32 v140, v239
	v_mov_b32_e32 v138, v240
	v_mov_b32_e32 v136, v241
	v_mov_b32_e32 v132, v242
	v_lshl_add_u64 v[156:157], v[134:135], 1, s[44:45]
	v_mov_b32_e32 v150, v243
	v_lshlrev_b64 v[134:135], 14, v[158:159]
	v_lshl_add_u64 v[134:135], v[156:157], 0, v[134:135]
	s_mov_b32 s7, 0x200000
	s_mov_b64 s[70:71], 0x200000
	s_waitcnt vmcnt(8)
	v_pk_mul_f32 v[110:111], v[110:111], v[152:153] op_sel_hi:[1,0]
	v_pk_mul_f32 v[102:103], v[102:103], v[152:153] op_sel_hi:[1,0]
	v_pk_mul_f32 v[94:95], v[94:95], v[160:161] op_sel_hi:[1,0]
	v_pk_mul_f32 v[86:87], v[86:87], v[160:161] op_sel_hi:[1,0]
	v_pk_mul_f32 v[78:79], v[78:79], v[142:143] op_sel_hi:[1,0]
	v_pk_mul_f32 v[70:71], v[70:71], v[142:143] op_sel_hi:[1,0]
	v_pk_mul_f32 v[62:63], v[62:63], v[140:141] op_sel_hi:[1,0]
	v_pk_mul_f32 v[54:55], v[54:55], v[140:141] op_sel_hi:[1,0]
	v_pk_mul_f32 v[162:163], v[122:123], v[150:151] op_sel_hi:[1,0]
	v_pk_mul_f32 v[122:123], v[120:121], v[150:151] op_sel_hi:[1,0]
	v_pk_mul_f32 v[120:121], v[124:125], v[150:151] op_sel_hi:[1,0]
	v_pk_mul_f32 v[126:127], v[126:127], v[150:151] op_sel_hi:[1,0]
	v_cvt_pk_bf16_f32 v120, v120, v121
	v_pk_mul_f32 v[118:119], v[118:119], v[150:151] op_sel_hi:[1,0]
	v_cvt_pk_bf16_f32 v121, v126, v127
	v_cvt_pk_bf16_f32 v122, v122, v123
	v_cvt_pk_bf16_f32 v123, v162, v163
	global_store_dwordx4 v[134:135], v[120:123], off
	v_pk_mul_f32 v[46:47], v[46:47], v[138:139] op_sel_hi:[1,0]
	v_pk_mul_f32 v[38:39], v[38:39], v[138:139] op_sel_hi:[1,0]
	v_pk_mul_f32 v[120:121], v[114:115], v[150:151] op_sel_hi:[1,0]
	v_pk_mul_f32 v[114:115], v[112:113], v[150:151] op_sel_hi:[1,0]
	v_pk_mul_f32 v[112:113], v[116:117], v[150:151] op_sel_hi:[1,0]
	v_pk_mul_f32 v[30:31], v[30:31], v[136:137] op_sel_hi:[1,0]
	v_cvt_pk_bf16_f32 v112, v112, v113
	v_cvt_pk_bf16_f32 v113, v118, v119
	v_cvt_pk_bf16_f32 v114, v114, v115
	v_cvt_pk_bf16_f32 v115, v120, v121
	global_store_dwordx4 v[134:135], v[112:115], off offset:256
	v_pk_mul_f32 v[22:23], v[22:23], v[136:137] op_sel_hi:[1,0]
	v_pk_mul_f32 v[14:15], v[14:15], v[132:133] op_sel_hi:[1,0]
	v_or_b32_e32 v112, 16, v158
	v_ashrrev_i32_e32 v113, 31, v112
	v_lshlrev_b64 v[112:113], 14, v[112:113]
	v_pk_mul_f32 v[114:115], v[106:107], v[152:153] op_sel_hi:[1,0]
	v_pk_mul_f32 v[106:107], v[104:105], v[152:153] op_sel_hi:[1,0]
	v_pk_mul_f32 v[104:105], v[108:109], v[152:153] op_sel_hi:[1,0]
	v_lshl_add_u64 v[112:113], v[156:157], 0, v[112:113]
	v_cvt_pk_bf16_f32 v104, v104, v105
	v_cvt_pk_bf16_f32 v105, v110, v111
	v_cvt_pk_bf16_f32 v106, v106, v107
	v_cvt_pk_bf16_f32 v107, v114, v115
	global_store_dwordx4 v[112:113], v[104:107], off
	v_pk_mul_f32 v[6:7], v[6:7], v[132:133] op_sel_hi:[1,0]
	s_nop 0
	v_pk_mul_f32 v[104:105], v[98:99], v[152:153] op_sel_hi:[1,0]
	v_pk_mul_f32 v[98:99], v[96:97], v[152:153] op_sel_hi:[1,0]
	v_pk_mul_f32 v[96:97], v[100:101], v[152:153] op_sel_hi:[1,0]
	s_nop 0
	v_cvt_pk_bf16_f32 v96, v96, v97
	v_cvt_pk_bf16_f32 v97, v102, v103
	v_cvt_pk_bf16_f32 v98, v98, v99
	v_cvt_pk_bf16_f32 v99, v104, v105
	global_store_dwordx4 v[112:113], v[96:99], off offset:256
	s_nop 1
	v_or_b32_e32 v96, 32, v158
	v_ashrrev_i32_e32 v97, 31, v96
	v_lshlrev_b64 v[96:97], 14, v[96:97]
	v_pk_mul_f32 v[98:99], v[90:91], v[160:161] op_sel_hi:[1,0]
	v_pk_mul_f32 v[90:91], v[88:89], v[160:161] op_sel_hi:[1,0]
	v_pk_mul_f32 v[88:89], v[92:93], v[160:161] op_sel_hi:[1,0]
	v_lshl_add_u64 v[96:97], v[156:157], 0, v[96:97]
	v_cvt_pk_bf16_f32 v88, v88, v89
	v_cvt_pk_bf16_f32 v89, v94, v95
	v_cvt_pk_bf16_f32 v90, v90, v91
	v_cvt_pk_bf16_f32 v91, v98, v99
	global_store_dwordx4 v[96:97], v[88:91], off
	s_nop 1
	v_pk_mul_f32 v[88:89], v[82:83], v[160:161] op_sel_hi:[1,0]
	v_pk_mul_f32 v[82:83], v[80:81], v[160:161] op_sel_hi:[1,0]
	v_pk_mul_f32 v[80:81], v[84:85], v[160:161] op_sel_hi:[1,0]
	s_nop 0
	v_cvt_pk_bf16_f32 v80, v80, v81
	v_cvt_pk_bf16_f32 v81, v86, v87
	v_cvt_pk_bf16_f32 v82, v82, v83
	v_cvt_pk_bf16_f32 v83, v88, v89
	global_store_dwordx4 v[96:97], v[80:83], off offset:256
	s_nop 1
	v_or_b32_e32 v80, 48, v158
	v_ashrrev_i32_e32 v81, 31, v80
	v_lshlrev_b64 v[80:81], 14, v[80:81]
	v_pk_mul_f32 v[82:83], v[74:75], v[142:143] op_sel_hi:[1,0]
	v_pk_mul_f32 v[74:75], v[72:73], v[142:143] op_sel_hi:[1,0]
	v_pk_mul_f32 v[72:73], v[76:77], v[142:143] op_sel_hi:[1,0]
	v_lshl_add_u64 v[80:81], v[156:157], 0, v[80:81]
	v_cvt_pk_bf16_f32 v72, v72, v73
	v_cvt_pk_bf16_f32 v73, v78, v79
	v_cvt_pk_bf16_f32 v74, v74, v75
	v_cvt_pk_bf16_f32 v75, v82, v83
	global_store_dwordx4 v[80:81], v[72:75], off
	s_nop 1
	v_pk_mul_f32 v[72:73], v[66:67], v[142:143] op_sel_hi:[1,0]
	v_pk_mul_f32 v[66:67], v[64:65], v[142:143] op_sel_hi:[1,0]
	v_pk_mul_f32 v[64:65], v[68:69], v[142:143] op_sel_hi:[1,0]
	s_nop 0
	v_cvt_pk_bf16_f32 v64, v64, v65
	v_cvt_pk_bf16_f32 v65, v70, v71
	v_cvt_pk_bf16_f32 v66, v66, v67
	v_cvt_pk_bf16_f32 v67, v72, v73
	global_store_dwordx4 v[80:81], v[64:67], off offset:256
	s_nop 1
	v_pk_mul_f32 v[66:67], v[58:59], v[140:141] op_sel_hi:[1,0]
	v_pk_mul_f32 v[58:59], v[56:57], v[140:141] op_sel_hi:[1,0]
	v_pk_mul_f32 v[56:57], v[60:61], v[140:141] op_sel_hi:[1,0]
	v_add_co_u32_e32 v60, vcc, s7, v134
	v_cvt_pk_bf16_f32 v56, v56, v57
	v_cvt_pk_bf16_f32 v57, v62, v63
	v_cvt_pk_bf16_f32 v58, v58, v59
	v_cvt_pk_bf16_f32 v59, v66, v67
	s_nop 1
	v_addc_co_u32_e32 v61, vcc, 0, v135, vcc
	global_store_dwordx4 v[60:61], v[56:59], off
	v_lshl_add_u64 v[64:65], v[134:135], 0, s[70:71]
	s_mov_b32 s7, 0x240000
	v_pk_mul_f32 v[56:57], v[50:51], v[140:141] op_sel_hi:[1,0]
	v_pk_mul_f32 v[50:51], v[48:49], v[140:141] op_sel_hi:[1,0]
	v_pk_mul_f32 v[48:49], v[52:53], v[140:141] op_sel_hi:[1,0]
	s_mov_b64 s[70:71], 0x240000
	v_cvt_pk_bf16_f32 v48, v48, v49
	v_cvt_pk_bf16_f32 v49, v54, v55
	v_cvt_pk_bf16_f32 v50, v50, v51
	v_cvt_pk_bf16_f32 v51, v56, v57
	global_store_dwordx4 v[64:65], v[48:51], off offset:256
	s_nop 1
	v_pk_mul_f32 v[50:51], v[42:43], v[138:139] op_sel_hi:[1,0]
	v_pk_mul_f32 v[42:43], v[40:41], v[138:139] op_sel_hi:[1,0]
	v_pk_mul_f32 v[40:41], v[44:45], v[138:139] op_sel_hi:[1,0]
	v_add_co_u32_e32 v44, vcc, s7, v134
	v_cvt_pk_bf16_f32 v40, v40, v41
	v_cvt_pk_bf16_f32 v41, v46, v47
	v_cvt_pk_bf16_f32 v42, v42, v43
	v_cvt_pk_bf16_f32 v43, v50, v51
	s_nop 1
	v_addc_co_u32_e32 v45, vcc, 0, v135, vcc
	global_store_dwordx4 v[44:45], v[40:43], off
	v_lshl_add_u64 v[48:49], v[134:135], 0, s[70:71]
	s_mov_b32 s7, 0x280000
	v_pk_mul_f32 v[40:41], v[34:35], v[138:139] op_sel_hi:[1,0]
	v_pk_mul_f32 v[34:35], v[32:33], v[138:139] op_sel_hi:[1,0]
	v_pk_mul_f32 v[32:33], v[36:37], v[138:139] op_sel_hi:[1,0]
	s_mov_b64 s[70:71], 0x280000
	v_cvt_pk_bf16_f32 v32, v32, v33
	v_cvt_pk_bf16_f32 v33, v38, v39
	v_cvt_pk_bf16_f32 v34, v34, v35
	v_cvt_pk_bf16_f32 v35, v40, v41
	global_store_dwordx4 v[48:49], v[32:35], off offset:256
	s_nop 1
	v_pk_mul_f32 v[34:35], v[26:27], v[136:137] op_sel_hi:[1,0]
	v_pk_mul_f32 v[26:27], v[24:25], v[136:137] op_sel_hi:[1,0]
	v_pk_mul_f32 v[24:25], v[28:29], v[136:137] op_sel_hi:[1,0]
	v_add_co_u32_e32 v28, vcc, s7, v134
	v_cvt_pk_bf16_f32 v24, v24, v25
	v_cvt_pk_bf16_f32 v25, v30, v31
	v_cvt_pk_bf16_f32 v26, v26, v27
	v_cvt_pk_bf16_f32 v27, v34, v35
	s_nop 1
	v_addc_co_u32_e32 v29, vcc, 0, v135, vcc
	global_store_dwordx4 v[28:29], v[24:27], off
	v_lshl_add_u64 v[32:33], v[134:135], 0, s[70:71]
	s_mov_b32 s7, 0x2c0000
	v_pk_mul_f32 v[24:25], v[18:19], v[136:137] op_sel_hi:[1,0]
	v_pk_mul_f32 v[18:19], v[16:17], v[136:137] op_sel_hi:[1,0]
	v_pk_mul_f32 v[16:17], v[20:21], v[136:137] op_sel_hi:[1,0]
	s_mov_b64 s[70:71], 0x2c0000
	v_cvt_pk_bf16_f32 v16, v16, v17
	v_cvt_pk_bf16_f32 v17, v22, v23
	v_cvt_pk_bf16_f32 v18, v18, v19
	v_cvt_pk_bf16_f32 v19, v24, v25
	global_store_dwordx4 v[32:33], v[16:19], off offset:256
	s_nop 1
	v_pk_mul_f32 v[18:19], v[10:11], v[132:133] op_sel_hi:[1,0]
	v_pk_mul_f32 v[10:11], v[8:9], v[132:133] op_sel_hi:[1,0]
	v_pk_mul_f32 v[8:9], v[12:13], v[132:133] op_sel_hi:[1,0]
	v_add_co_u32_e32 v12, vcc, s7, v134
	v_cvt_pk_bf16_f32 v8, v8, v9
	v_cvt_pk_bf16_f32 v9, v14, v15
	v_lshl_add_u64 v[16:17], v[134:135], 0, s[70:71]
	s_nop 0
	v_addc_co_u32_e32 v13, vcc, 0, v135, vcc
	v_cvt_pk_bf16_f32 v10, v10, v11
	v_cvt_pk_bf16_f32 v11, v18, v19
	global_store_dwordx4 v[12:13], v[8:11], off
	s_mov_b64 s[70:71], -1
	s_andn2_b64 vcc, exec, s[52:53]
	v_pk_mul_f32 v[8:9], v[2:3], v[132:133] op_sel_hi:[1,0]
	v_pk_mul_f32 v[2:3], v[0:1], v[132:133] op_sel_hi:[1,0]
	v_pk_mul_f32 v[0:1], v[4:5], v[132:133] op_sel_hi:[1,0]
	s_nop 0
	v_cvt_pk_bf16_f32 v0, v0, v1
	v_cvt_pk_bf16_f32 v1, v6, v7
	v_cvt_pk_bf16_f32 v2, v2, v3
	v_cvt_pk_bf16_f32 v3, v8, v9
	global_store_dwordx4 v[16:17], v[0:3], off offset:256
	s_cbranch_vccnz .LBB0_161
	s_andn2_b64 vcc, exec, s[2:3]
	s_cbranch_vccnz .LBB0_160
	s_barrier
	s_branch .LBB0_160

.LBB0_332:
	v_lshl_add_u32 v244, s84, 8, v133
	v_readlane_b32 s100, v253, 49
	v_ashrrev_i32_e32 v245, 31, v244
	v_readlane_b32 s101, v253, 50
	s_nop 1
	v_lshl_add_u64 v[244:245], v[244:245], 2, s[100:101]
	global_load_dword v236, v[244:245], off offset:64
	global_load_dword v237, v[244:245], off offset:128
	global_load_dword v238, v[244:245], off offset:192
	global_load_dword v239, v[244:245], off offset:512
	global_load_dword v240, v[244:245], off offset:576
	global_load_dword v241, v[244:245], off offset:640
	global_load_dword v242, v[244:245], off offset:704
	global_load_dword v243, v[244:245], off
	s_ashr_i32 s47, s46, 31
	s_lshl_b64 s[68:69], s[46:47], 21
	s_add_u32 s68, s39, s68
	s_addc_u32 s69, s43, s69
	s_and_b64 s[74:75], s[52:53], exec
	s_cselect_b32 s42, s69, s71
	s_cselect_b32 s47, s68, s70
	s_ashr_i32 s7, s6, 31
	s_lshl_b64 s[74:75], s[6:7], 21
	s_add_u32 s78, s37, s74
	s_addc_u32 s79, s38, s75
	s_and_b64 s[74:75], s[52:53], exec
	s_cselect_b32 s7, s79, s73
	s_cselect_b32 s74, s78, s72
	s_add_u32 s70, s70, 0x100080
	s_addc_u32 s71, s71, 0
	s_add_u32 s75, s72, 0x100
	v_mov_b32_e32 v0, 0
	s_addc_u32 s77, s73, 0
	s_mov_b32 s81, -2
	v_mov_b32_e32 v1, v0
	v_mov_b32_e32 v2, v0
	v_mov_b32_e32 v3, v0
	v_mov_b32_e32 v4, v0
	v_mov_b32_e32 v5, v0
	v_mov_b32_e32 v6, v0
	v_mov_b32_e32 v7, v0
	v_mov_b32_e32 v16, v0
	v_mov_b32_e32 v17, v0
	v_mov_b32_e32 v18, v0
	v_mov_b32_e32 v19, v0
	v_mov_b32_e32 v20, v0
	v_mov_b32_e32 v21, v0
	v_mov_b32_e32 v22, v0
	v_mov_b32_e32 v23, v0
	v_mov_b32_e32 v32, v0
	v_mov_b32_e32 v33, v0
	v_mov_b32_e32 v34, v0
	v_mov_b32_e32 v35, v0
	v_mov_b32_e32 v36, v0
	v_mov_b32_e32 v37, v0
	v_mov_b32_e32 v38, v0
	v_mov_b32_e32 v39, v0
	v_mov_b32_e32 v48, v0
	v_mov_b32_e32 v49, v0
	v_mov_b32_e32 v50, v0
	v_mov_b32_e32 v51, v0
	v_mov_b32_e32 v52, v0
	v_mov_b32_e32 v53, v0
	v_mov_b32_e32 v54, v0
	v_mov_b32_e32 v55, v0
	v_mov_b32_e32 v8, v0
	v_mov_b32_e32 v9, v0
	v_mov_b32_e32 v10, v0
	v_mov_b32_e32 v11, v0
	v_mov_b32_e32 v12, v0
	v_mov_b32_e32 v13, v0
	v_mov_b32_e32 v14, v0
	v_mov_b32_e32 v15, v0
	v_mov_b32_e32 v24, v0
	v_mov_b32_e32 v25, v0
	v_mov_b32_e32 v26, v0
	v_mov_b32_e32 v27, v0
	v_mov_b32_e32 v28, v0
	v_mov_b32_e32 v29, v0
	v_mov_b32_e32 v30, v0
	v_mov_b32_e32 v31, v0
	v_mov_b32_e32 v40, v0
	v_mov_b32_e32 v41, v0
	v_mov_b32_e32 v42, v0
	v_mov_b32_e32 v43, v0
	v_mov_b32_e32 v44, v0
	v_mov_b32_e32 v45, v0
	v_mov_b32_e32 v46, v0
	v_mov_b32_e32 v47, v0
	v_mov_b32_e32 v56, v0
	v_mov_b32_e32 v57, v0
	v_mov_b32_e32 v58, v0
	v_mov_b32_e32 v59, v0
	v_mov_b32_e32 v60, v0
	v_mov_b32_e32 v61, v0
	v_mov_b32_e32 v62, v0
	v_mov_b32_e32 v63, v0
	v_mov_b32_e32 v64, v0
	v_mov_b32_e32 v65, v0
	v_mov_b32_e32 v66, v0
	v_mov_b32_e32 v67, v0
	v_mov_b32_e32 v68, v0
	v_mov_b32_e32 v69, v0
	v_mov_b32_e32 v70, v0
	v_mov_b32_e32 v71, v0
	v_mov_b32_e32 v80, v0
	v_mov_b32_e32 v81, v0
	v_mov_b32_e32 v82, v0
	v_mov_b32_e32 v83, v0
	v_mov_b32_e32 v84, v0
	v_mov_b32_e32 v85, v0
	v_mov_b32_e32 v86, v0
	v_mov_b32_e32 v87, v0
	v_mov_b32_e32 v96, v0
	v_mov_b32_e32 v97, v0
	v_mov_b32_e32 v98, v0
	v_mov_b32_e32 v99, v0
	v_mov_b32_e32 v100, v0
	v_mov_b32_e32 v101, v0
	v_mov_b32_e32 v102, v0
	v_mov_b32_e32 v103, v0
	v_mov_b32_e32 v112, v0
	v_mov_b32_e32 v113, v0
	v_mov_b32_e32 v114, v0
	v_mov_b32_e32 v115, v0
	v_mov_b32_e32 v116, v0
	v_mov_b32_e32 v117, v0
	v_mov_b32_e32 v118, v0
	v_mov_b32_e32 v119, v0
	v_mov_b32_e32 v72, v0
	v_mov_b32_e32 v73, v0
	v_mov_b32_e32 v74, v0
	v_mov_b32_e32 v75, v0
	v_mov_b32_e32 v76, v0
	v_mov_b32_e32 v77, v0
	v_mov_b32_e32 v78, v0
	v_mov_b32_e32 v79, v0
	v_mov_b32_e32 v88, v0
	v_mov_b32_e32 v89, v0
	v_mov_b32_e32 v90, v0
	v_mov_b32_e32 v91, v0
	v_mov_b32_e32 v92, v0
	v_mov_b32_e32 v93, v0
	v_mov_b32_e32 v94, v0
	v_mov_b32_e32 v95, v0
	v_mov_b32_e32 v104, v0
	v_mov_b32_e32 v105, v0
	v_mov_b32_e32 v106, v0
	v_mov_b32_e32 v107, v0
	v_mov_b32_e32 v108, v0
	v_mov_b32_e32 v109, v0
	v_mov_b32_e32 v110, v0
	v_mov_b32_e32 v111, v0
	v_mov_b32_e32 v120, v0
	v_mov_b32_e32 v121, v0
	v_mov_b32_e32 v122, v0
	v_mov_b32_e32 v123, v0
	v_mov_b32_e32 v124, v0
	v_mov_b32_e32 v125, v0
	v_mov_b32_e32 v126, v0
	v_mov_b32_e32 v127, v0

.LBB0_336:
	v_lshl_add_u32 v158, s84, 8, v133
	v_readlane_b32 s70, v253, 49
	v_ashrrev_i32_e32 v159, 31, v158
	v_readlane_b32 s71, v253, 50
	v_lshl_or_b32 v134, s80, 8, v139
	v_ashrrev_i32_e32 v135, 31, v134
	v_mov_b32_e32 v152, v236
	v_mov_b32_e32 v160, v237
	v_mov_b32_e32 v142, v238
	v_mov_b32_e32 v140, v239
	v_mov_b32_e32 v138, v240
	v_mov_b32_e32 v136, v241
	v_mov_b32_e32 v132, v242
	v_lshl_add_u64 v[156:157], v[134:135], 1, s[44:45]
	v_mov_b32_e32 v150, v243
	v_lshlrev_b64 v[134:135], 14, v[158:159]
	v_lshl_add_u64 v[134:135], v[156:157], 0, v[134:135]
	s_mov_b32 s7, 0x200000
	s_mov_b64 s[70:71], 0x200000
	s_waitcnt vmcnt(8)
	v_pk_mul_f32 v[110:111], v[110:111], v[152:153] op_sel_hi:[1,0]
	v_pk_mul_f32 v[102:103], v[102:103], v[152:153] op_sel_hi:[1,0]
	v_pk_mul_f32 v[94:95], v[94:95], v[160:161] op_sel_hi:[1,0]
	v_pk_mul_f32 v[86:87], v[86:87], v[160:161] op_sel_hi:[1,0]
	v_pk_mul_f32 v[78:79], v[78:79], v[142:143] op_sel_hi:[1,0]
	v_pk_mul_f32 v[70:71], v[70:71], v[142:143] op_sel_hi:[1,0]
	v_pk_mul_f32 v[62:63], v[62:63], v[140:141] op_sel_hi:[1,0]
	v_pk_mul_f32 v[54:55], v[54:55], v[140:141] op_sel_hi:[1,0]
	v_pk_mul_f32 v[162:163], v[122:123], v[150:151] op_sel_hi:[1,0]
	v_pk_mul_f32 v[122:123], v[120:121], v[150:151] op_sel_hi:[1,0]
	v_pk_mul_f32 v[120:121], v[124:125], v[150:151] op_sel_hi:[1,0]
	v_pk_mul_f32 v[126:127], v[126:127], v[150:151] op_sel_hi:[1,0]
	v_cvt_pk_bf16_f32 v120, v120, v121
	v_pk_mul_f32 v[118:119], v[118:119], v[150:151] op_sel_hi:[1,0]
	v_cvt_pk_bf16_f32 v121, v126, v127
	v_cvt_pk_bf16_f32 v122, v122, v123
	v_cvt_pk_bf16_f32 v123, v162, v163
	global_store_dwordx4 v[134:135], v[120:123], off
	v_pk_mul_f32 v[46:47], v[46:47], v[138:139] op_sel_hi:[1,0]
	v_pk_mul_f32 v[38:39], v[38:39], v[138:139] op_sel_hi:[1,0]
	v_pk_mul_f32 v[120:121], v[114:115], v[150:151] op_sel_hi:[1,0]
	v_pk_mul_f32 v[114:115], v[112:113], v[150:151] op_sel_hi:[1,0]
	v_pk_mul_f32 v[112:113], v[116:117], v[150:151] op_sel_hi:[1,0]
	v_pk_mul_f32 v[30:31], v[30:31], v[136:137] op_sel_hi:[1,0]
	v_cvt_pk_bf16_f32 v112, v112, v113
	v_cvt_pk_bf16_f32 v113, v118, v119
	v_cvt_pk_bf16_f32 v114, v114, v115
	v_cvt_pk_bf16_f32 v115, v120, v121
	global_store_dwordx4 v[134:135], v[112:115], off offset:256
	v_pk_mul_f32 v[22:23], v[22:23], v[136:137] op_sel_hi:[1,0]
	v_pk_mul_f32 v[14:15], v[14:15], v[132:133] op_sel_hi:[1,0]
	v_or_b32_e32 v112, 16, v158
	v_ashrrev_i32_e32 v113, 31, v112
	v_lshlrev_b64 v[112:113], 14, v[112:113]
	v_pk_mul_f32 v[114:115], v[106:107], v[152:153] op_sel_hi:[1,0]
	v_pk_mul_f32 v[106:107], v[104:105], v[152:153] op_sel_hi:[1,0]
	v_pk_mul_f32 v[104:105], v[108:109], v[152:153] op_sel_hi:[1,0]
	v_lshl_add_u64 v[112:113], v[156:157], 0, v[112:113]
	v_cvt_pk_bf16_f32 v104, v104, v105
	v_cvt_pk_bf16_f32 v105, v110, v111
	v_cvt_pk_bf16_f32 v106, v106, v107
	v_cvt_pk_bf16_f32 v107, v114, v115
	global_store_dwordx4 v[112:113], v[104:107], off
	v_pk_mul_f32 v[6:7], v[6:7], v[132:133] op_sel_hi:[1,0]
	s_nop 0
	v_pk_mul_f32 v[104:105], v[98:99], v[152:153] op_sel_hi:[1,0]
	v_pk_mul_f32 v[98:99], v[96:97], v[152:153] op_sel_hi:[1,0]
	v_pk_mul_f32 v[96:97], v[100:101], v[152:153] op_sel_hi:[1,0]
	s_nop 0
	v_cvt_pk_bf16_f32 v96, v96, v97
	v_cvt_pk_bf16_f32 v97, v102, v103
	v_cvt_pk_bf16_f32 v98, v98, v99
	v_cvt_pk_bf16_f32 v99, v104, v105
	global_store_dwordx4 v[112:113], v[96:99], off offset:256
	s_nop 1
	v_or_b32_e32 v96, 32, v158
	v_ashrrev_i32_e32 v97, 31, v96
	v_lshlrev_b64 v[96:97], 14, v[96:97]
	v_pk_mul_f32 v[98:99], v[90:91], v[160:161] op_sel_hi:[1,0]
	v_pk_mul_f32 v[90:91], v[88:89], v[160:161] op_sel_hi:[1,0]
	v_pk_mul_f32 v[88:89], v[92:93], v[160:161] op_sel_hi:[1,0]
	v_lshl_add_u64 v[96:97], v[156:157], 0, v[96:97]
	v_cvt_pk_bf16_f32 v88, v88, v89
	v_cvt_pk_bf16_f32 v89, v94, v95
	v_cvt_pk_bf16_f32 v90, v90, v91
	v_cvt_pk_bf16_f32 v91, v98, v99
	global_store_dwordx4 v[96:97], v[88:91], off
	s_nop 1
	v_pk_mul_f32 v[88:89], v[82:83], v[160:161] op_sel_hi:[1,0]
	v_pk_mul_f32 v[82:83], v[80:81], v[160:161] op_sel_hi:[1,0]
	v_pk_mul_f32 v[80:81], v[84:85], v[160:161] op_sel_hi:[1,0]
	s_nop 0
	v_cvt_pk_bf16_f32 v80, v80, v81
	v_cvt_pk_bf16_f32 v81, v86, v87
	v_cvt_pk_bf16_f32 v82, v82, v83
	v_cvt_pk_bf16_f32 v83, v88, v89
	global_store_dwordx4 v[96:97], v[80:83], off offset:256
	s_nop 1
	v_or_b32_e32 v80, 48, v158
	v_ashrrev_i32_e32 v81, 31, v80
	v_lshlrev_b64 v[80:81], 14, v[80:81]
	v_pk_mul_f32 v[82:83], v[74:75], v[142:143] op_sel_hi:[1,0]
	v_pk_mul_f32 v[74:75], v[72:73], v[142:143] op_sel_hi:[1,0]
	v_pk_mul_f32 v[72:73], v[76:77], v[142:143] op_sel_hi:[1,0]
	v_lshl_add_u64 v[80:81], v[156:157], 0, v[80:81]
	v_cvt_pk_bf16_f32 v72, v72, v73
	v_cvt_pk_bf16_f32 v73, v78, v79
	v_cvt_pk_bf16_f32 v74, v74, v75
	v_cvt_pk_bf16_f32 v75, v82, v83
	global_store_dwordx4 v[80:81], v[72:75], off
	s_nop 1
	v_pk_mul_f32 v[72:73], v[66:67], v[142:143] op_sel_hi:[1,0]
	v_pk_mul_f32 v[66:67], v[64:65], v[142:143] op_sel_hi:[1,0]
	v_pk_mul_f32 v[64:65], v[68:69], v[142:143] op_sel_hi:[1,0]
	s_nop 0
	v_cvt_pk_bf16_f32 v64, v64, v65
	v_cvt_pk_bf16_f32 v65, v70, v71
	v_cvt_pk_bf16_f32 v66, v66, v67
	v_cvt_pk_bf16_f32 v67, v72, v73
	global_store_dwordx4 v[80:81], v[64:67], off offset:256
	s_nop 1
	v_pk_mul_f32 v[66:67], v[58:59], v[140:141] op_sel_hi:[1,0]
	v_pk_mul_f32 v[58:59], v[56:57], v[140:141] op_sel_hi:[1,0]
	v_pk_mul_f32 v[56:57], v[60:61], v[140:141] op_sel_hi:[1,0]
	v_add_co_u32_e32 v60, vcc, s7, v134
	v_cvt_pk_bf16_f32 v56, v56, v57
	v_cvt_pk_bf16_f32 v57, v62, v63
	v_cvt_pk_bf16_f32 v58, v58, v59
	v_cvt_pk_bf16_f32 v59, v66, v67
	s_nop 1
	v_addc_co_u32_e32 v61, vcc, 0, v135, vcc
	global_store_dwordx4 v[60:61], v[56:59], off
	v_lshl_add_u64 v[64:65], v[134:135], 0, s[70:71]
	s_mov_b32 s7, 0x240000
	v_pk_mul_f32 v[56:57], v[50:51], v[140:141] op_sel_hi:[1,0]
	v_pk_mul_f32 v[50:51], v[48:49], v[140:141] op_sel_hi:[1,0]
	v_pk_mul_f32 v[48:49], v[52:53], v[140:141] op_sel_hi:[1,0]
	s_mov_b64 s[70:71], 0x240000
	v_cvt_pk_bf16_f32 v48, v48, v49
	v_cvt_pk_bf16_f32 v49, v54, v55
	v_cvt_pk_bf16_f32 v50, v50, v51
	v_cvt_pk_bf16_f32 v51, v56, v57
	global_store_dwordx4 v[64:65], v[48:51], off offset:256
	s_nop 1
	v_pk_mul_f32 v[50:51], v[42:43], v[138:139] op_sel_hi:[1,0]
	v_pk_mul_f32 v[42:43], v[40:41], v[138:139] op_sel_hi:[1,0]
	v_pk_mul_f32 v[40:41], v[44:45], v[138:139] op_sel_hi:[1,0]
	v_add_co_u32_e32 v44, vcc, s7, v134
	v_cvt_pk_bf16_f32 v40, v40, v41
	v_cvt_pk_bf16_f32 v41, v46, v47
	v_cvt_pk_bf16_f32 v42, v42, v43
	v_cvt_pk_bf16_f32 v43, v50, v51
	s_nop 1
	v_addc_co_u32_e32 v45, vcc, 0, v135, vcc
	global_store_dwordx4 v[44:45], v[40:43], off
	v_lshl_add_u64 v[48:49], v[134:135], 0, s[70:71]
	s_mov_b32 s7, 0x280000
	v_pk_mul_f32 v[40:41], v[34:35], v[138:139] op_sel_hi:[1,0]
	v_pk_mul_f32 v[34:35], v[32:33], v[138:139] op_sel_hi:[1,0]
	v_pk_mul_f32 v[32:33], v[36:37], v[138:139] op_sel_hi:[1,0]
	s_mov_b64 s[70:71], 0x280000
	v_cvt_pk_bf16_f32 v32, v32, v33
	v_cvt_pk_bf16_f32 v33, v38, v39
	v_cvt_pk_bf16_f32 v34, v34, v35
	v_cvt_pk_bf16_f32 v35, v40, v41
	global_store_dwordx4 v[48:49], v[32:35], off offset:256
	s_nop 1
	v_pk_mul_f32 v[34:35], v[26:27], v[136:137] op_sel_hi:[1,0]
	v_pk_mul_f32 v[26:27], v[24:25], v[136:137] op_sel_hi:[1,0]
	v_pk_mul_f32 v[24:25], v[28:29], v[136:137] op_sel_hi:[1,0]
	v_add_co_u32_e32 v28, vcc, s7, v134
	v_cvt_pk_bf16_f32 v24, v24, v25
	v_cvt_pk_bf16_f32 v25, v30, v31
	v_cvt_pk_bf16_f32 v26, v26, v27
	v_cvt_pk_bf16_f32 v27, v34, v35
	s_nop 1
	v_addc_co_u32_e32 v29, vcc, 0, v135, vcc
	global_store_dwordx4 v[28:29], v[24:27], off
	v_lshl_add_u64 v[32:33], v[134:135], 0, s[70:71]
	s_mov_b32 s7, 0x2c0000
	v_pk_mul_f32 v[24:25], v[18:19], v[136:137] op_sel_hi:[1,0]
	v_pk_mul_f32 v[18:19], v[16:17], v[136:137] op_sel_hi:[1,0]
	v_pk_mul_f32 v[16:17], v[20:21], v[136:137] op_sel_hi:[1,0]
	s_mov_b64 s[70:71], 0x2c0000
	v_cvt_pk_bf16_f32 v16, v16, v17
	v_cvt_pk_bf16_f32 v17, v22, v23
	v_cvt_pk_bf16_f32 v18, v18, v19
	v_cvt_pk_bf16_f32 v19, v24, v25
	global_store_dwordx4 v[32:33], v[16:19], off offset:256
	s_nop 1
	v_pk_mul_f32 v[18:19], v[10:11], v[132:133] op_sel_hi:[1,0]
	v_pk_mul_f32 v[10:11], v[8:9], v[132:133] op_sel_hi:[1,0]
	v_pk_mul_f32 v[8:9], v[12:13], v[132:133] op_sel_hi:[1,0]
	v_add_co_u32_e32 v12, vcc, s7, v134
	v_cvt_pk_bf16_f32 v8, v8, v9
	v_cvt_pk_bf16_f32 v9, v14, v15
	v_lshl_add_u64 v[16:17], v[134:135], 0, s[70:71]
	s_nop 0
	v_addc_co_u32_e32 v13, vcc, 0, v135, vcc
	v_cvt_pk_bf16_f32 v10, v10, v11
	v_cvt_pk_bf16_f32 v11, v18, v19
	global_store_dwordx4 v[12:13], v[8:11], off
	s_mov_b64 s[70:71], -1
	s_andn2_b64 vcc, exec, s[52:53]
	v_pk_mul_f32 v[8:9], v[2:3], v[132:133] op_sel_hi:[1,0]
	v_pk_mul_f32 v[2:3], v[0:1], v[132:133] op_sel_hi:[1,0]
	v_pk_mul_f32 v[0:1], v[4:5], v[132:133] op_sel_hi:[1,0]
	s_nop 0
	v_cvt_pk_bf16_f32 v0, v0, v1
	v_cvt_pk_bf16_f32 v1, v6, v7
	v_cvt_pk_bf16_f32 v2, v2, v3
	v_cvt_pk_bf16_f32 v3, v8, v9
	global_store_dwordx4 v[16:17], v[0:3], off offset:256
	s_cbranch_vccnz .LBB0_324
	s_andn2_b64 vcc, exec, s[2:3]
	s_cbranch_vccnz .LBB0_323
	s_barrier
	s_branch .LBB0_323

.LBB0_1402:
	v_lshl_add_u32 v244, s26, 8, v156
	v_readlane_b32 s100, v253, 49
	v_ashrrev_i32_e32 v245, 31, v244
	v_readlane_b32 s101, v253, 50
	s_nop 1
	v_lshl_add_u64 v[244:245], v[244:245], 2, s[100:101]
	global_load_dword v236, v[244:245], off
	global_load_dword v237, v[244:245], off offset:64
	global_load_dword v238, v[244:245], off offset:128
	global_load_dword v239, v[244:245], off offset:192
	global_load_dword v240, v[244:245], off offset:512
	global_load_dword v241, v[244:245], off offset:576
	global_load_dword v242, v[244:245], off offset:640
	global_load_dword v243, v[244:245], off offset:704
	s_ashr_i32 s15, s14, 31
	s_lshl_b64 s[16:17], s[14:15], 21
	s_add_u32 s16, s43, s16
	s_addc_u32 s17, s44, s17
	s_and_b64 s[18:19], s[2:3], exec
	s_cselect_b32 s5, s17, s37
	s_cselect_b32 s15, s16, s36
	s_ashr_i32 s13, s12, 31
	s_lshl_b64 s[18:19], s[12:13], 21
	s_add_u32 s18, s41, s18
	s_addc_u32 s19, s42, s19
	s_and_b64 s[58:59], s[2:3], exec
	s_cselect_b32 s13, s19, s39
	s_cselect_b32 s27, s18, s38
	s_add_u32 s36, s36, 0x100080
	s_addc_u32 s37, s37, 0
	s_add_u32 s58, s38, 0x100
	v_mov_b32_e32 v2, 0
	s_addc_u32 s59, s39, 0
	s_mov_b32 s60, -2
	v_mov_b32_e32 v3, v2
	v_mov_b32_e32 v4, v2
	v_mov_b32_e32 v5, v2
	v_mov_b32_e32 v6, v2
	v_mov_b32_e32 v7, v2
	v_mov_b32_e32 v8, v2
	v_mov_b32_e32 v9, v2
	v_mov_b32_e32 v18, v2
	v_mov_b32_e32 v19, v2
	v_mov_b32_e32 v20, v2
	v_mov_b32_e32 v21, v2
	v_mov_b32_e32 v22, v2
	v_mov_b32_e32 v23, v2
	v_mov_b32_e32 v24, v2
	v_mov_b32_e32 v25, v2
	v_mov_b32_e32 v34, v2
	v_mov_b32_e32 v35, v2
	v_mov_b32_e32 v36, v2
	v_mov_b32_e32 v37, v2
	v_mov_b32_e32 v38, v2
	v_mov_b32_e32 v39, v2
	v_mov_b32_e32 v40, v2
	v_mov_b32_e32 v41, v2
	v_mov_b32_e32 v50, v2
	v_mov_b32_e32 v51, v2
	v_mov_b32_e32 v52, v2
	v_mov_b32_e32 v53, v2
	v_mov_b32_e32 v54, v2
	v_mov_b32_e32 v55, v2
	v_mov_b32_e32 v56, v2
	v_mov_b32_e32 v57, v2
	v_mov_b32_e32 v10, v2
	v_mov_b32_e32 v11, v2
	v_mov_b32_e32 v12, v2
	v_mov_b32_e32 v13, v2
	v_mov_b32_e32 v14, v2
	v_mov_b32_e32 v15, v2
	v_mov_b32_e32 v16, v2
	v_mov_b32_e32 v17, v2
	v_mov_b32_e32 v26, v2
	v_mov_b32_e32 v27, v2
	v_mov_b32_e32 v28, v2
	v_mov_b32_e32 v29, v2
	v_mov_b32_e32 v30, v2
	v_mov_b32_e32 v31, v2
	v_mov_b32_e32 v32, v2
	v_mov_b32_e32 v33, v2
	v_mov_b32_e32 v42, v2
	v_mov_b32_e32 v43, v2
	v_mov_b32_e32 v44, v2
	v_mov_b32_e32 v45, v2
	v_mov_b32_e32 v46, v2
	v_mov_b32_e32 v47, v2
	v_mov_b32_e32 v48, v2
	v_mov_b32_e32 v49, v2
	v_mov_b32_e32 v58, v2
	v_mov_b32_e32 v59, v2
	v_mov_b32_e32 v60, v2
	v_mov_b32_e32 v61, v2
	v_mov_b32_e32 v62, v2
	v_mov_b32_e32 v63, v2
	v_mov_b32_e32 v64, v2
	v_mov_b32_e32 v65, v2
	v_mov_b32_e32 v66, v2
	v_mov_b32_e32 v67, v2
	v_mov_b32_e32 v68, v2
	v_mov_b32_e32 v69, v2
	v_mov_b32_e32 v70, v2
	v_mov_b32_e32 v71, v2
	v_mov_b32_e32 v72, v2
	v_mov_b32_e32 v73, v2
	v_mov_b32_e32 v82, v2
	v_mov_b32_e32 v83, v2
	v_mov_b32_e32 v84, v2
	v_mov_b32_e32 v85, v2
	v_mov_b32_e32 v86, v2
	v_mov_b32_e32 v87, v2
	v_mov_b32_e32 v88, v2
	v_mov_b32_e32 v89, v2
	v_mov_b32_e32 v98, v2
	v_mov_b32_e32 v99, v2
	v_mov_b32_e32 v100, v2
	v_mov_b32_e32 v101, v2
	v_mov_b32_e32 v102, v2
	v_mov_b32_e32 v103, v2
	v_mov_b32_e32 v104, v2
	v_mov_b32_e32 v105, v2
	v_mov_b32_e32 v114, v2
	v_mov_b32_e32 v115, v2
	v_mov_b32_e32 v116, v2
	v_mov_b32_e32 v117, v2
	v_mov_b32_e32 v118, v2
	v_mov_b32_e32 v119, v2
	v_mov_b32_e32 v120, v2
	v_mov_b32_e32 v121, v2
	v_mov_b32_e32 v74, v2
	v_mov_b32_e32 v75, v2
	v_mov_b32_e32 v76, v2
	v_mov_b32_e32 v77, v2
	v_mov_b32_e32 v78, v2
	v_mov_b32_e32 v79, v2
	v_mov_b32_e32 v80, v2
	v_mov_b32_e32 v81, v2
	v_mov_b32_e32 v90, v2
	v_mov_b32_e32 v91, v2
	v_mov_b32_e32 v92, v2
	v_mov_b32_e32 v93, v2
	v_mov_b32_e32 v94, v2
	v_mov_b32_e32 v95, v2
	v_mov_b32_e32 v96, v2
	v_mov_b32_e32 v97, v2
	v_mov_b32_e32 v106, v2
	v_mov_b32_e32 v107, v2
	v_mov_b32_e32 v108, v2
	v_mov_b32_e32 v109, v2
	v_mov_b32_e32 v110, v2
	v_mov_b32_e32 v111, v2
	v_mov_b32_e32 v112, v2
	v_mov_b32_e32 v113, v2
	v_mov_b32_e32 v122, v2
	v_mov_b32_e32 v123, v2
	v_mov_b32_e32 v124, v2
	v_mov_b32_e32 v125, v2
	v_mov_b32_e32 v126, v2
	v_mov_b32_e32 v127, v2
	v_mov_b32_e32 v128, v2
	v_mov_b32_e32 v129, v2

.LBB0_1406:
	v_lshl_add_u32 v136, s26, 8, v156
	v_readlane_b32 s26, v253, 49
	v_ashrrev_i32_e32 v137, 31, v136
	v_readlane_b32 s27, v253, 50
	s_cmp_lt_i32 s4, 16
	s_cselect_b64 s[36:37], -1, 0
	v_mov_b32_e32 v150, v236
	v_mov_b32_e32 v148, v237
	v_mov_b32_e32 v146, v238
	v_mov_b32_e32 v144, v239
	v_mov_b32_e32 v142, v240
	v_mov_b32_e32 v140, v241
	v_mov_b32_e32 v138, v242
	s_nop 0
	v_mov_b32_e32 v134, v243
	s_cmp_gt_i32 s4, 15
	s_cselect_b64 s[26:27], -1, 0
	s_and_b64 vcc, exec, s[36:37]
	s_waitcnt vmcnt(8)
	v_pk_mul_f32 v[152:153], v[128:129], v[150:151] op_sel_hi:[1,0]
	v_pk_mul_f32 v[154:155], v[126:127], v[150:151] op_sel_hi:[1,0]
	v_pk_mul_f32 v[126:127], v[124:125], v[150:151] op_sel_hi:[1,0]
	v_pk_mul_f32 v[128:129], v[122:123], v[150:151] op_sel_hi:[1,0]
	s_cbranch_vccnz .LBB0_1408
	v_mul_f32_e32 v123, 0xbfb8aa3b, v128
	v_exp_f32_e32 v123, v123
	v_mul_f32_e32 v135, 0xbfb8aa3b, v152
	v_exp_f32_e32 v135, v135
	v_mul_f32_e32 v122, 0xbfb8aa3b, v154
	v_add_f32_e32 v123, 1.0, v123
	v_rcp_f32_e32 v124, v123
	v_mul_f32_e32 v123, 0xbfb8aa3b, v155
	v_exp_f32_e32 v122, v122
	v_exp_f32_e32 v123, v123
	v_add_f32_e32 v135, 1.0, v135
	v_rcp_f32_e32 v164, v135
	v_mul_f32_e32 v135, 0xbfb8aa3b, v126
	v_add_f32_e32 v122, 1.0, v122
	v_add_f32_e32 v123, 1.0, v123
	v_exp_f32_e32 v135, v135
	v_rcp_f32_e32 v122, v122
	v_rcp_f32_e32 v123, v123
	v_mul_f32_e32 v125, 0xbfb8aa3b, v129
	v_add_f32_e32 v135, 1.0, v135
	v_rcp_f32_e32 v166, v135
	v_mul_f32_e32 v135, 0xbfb8aa3b, v153
	v_pk_mul_f32 v[154:155], v[154:155], v[122:123]
	v_mul_f32_e32 v122, 0xbfb8aa3b, v127
	v_exp_f32_e32 v125, v125
	v_exp_f32_e32 v135, v135
	v_exp_f32_e32 v122, v122
	v_add_f32_e32 v125, 1.0, v125
	v_add_f32_e32 v135, 1.0, v135
	v_add_f32_e32 v122, 1.0, v122
	v_rcp_f32_e32 v125, v125
	v_rcp_f32_e32 v165, v135
	v_rcp_f32_e32 v167, v122
	v_pk_mul_f32 v[128:129], v[128:129], v[124:125]
	v_pk_mul_f32 v[152:153], v[152:153], v[164:165]
	v_pk_mul_f32 v[126:127], v[126:127], v[166:167]
